# P1 rope tiles: rope-table loads hoisted to the epilogue top, counted waits leave stores in flight
# baseline (speedup 1.0000x reference)
.LBB0_256:
	s_andn2_b64 vcc, exec, s[2:3]
	s_cbranch_vccnz .LBB0_291
	v_lshlrev_b32_e32 v148, 3, v160
	v_and_or_b32 v148, v148, s53, v155
	v_lshlrev_b32_e32 v148, 5, v148
	global_load_dwordx4 v[162:165], v148, s[14:15] offset:16
	global_load_dwordx4 v[166:169], v148, s[14:15]
	v_add_u32_e32 v247, 0x1000, v148
	global_load_dwordx4 v[188:191], v247, s[14:15] offset:16
	global_load_dwordx4 v[192:195], v247, s[14:15]
	v_add_u32_e32 v247, 0x2000, v148
	global_load_dwordx4 v[196:199], v247, s[14:15] offset:16
	global_load_dwordx4 v[200:203], v247, s[14:15]
	v_add_u32_e32 v247, 0x3000, v148
	global_load_dwordx4 v[204:207], v247, s[14:15] offset:16
	global_load_dwordx4 v[208:211], v247, s[14:15]
	v_add_u32_e32 v247, 0x8000, v148
	global_load_dwordx4 v[216:219], v247, s[14:15] offset:16
	global_load_dwordx4 v[220:223], v247, s[14:15]
	v_add_u32_e32 v247, 0x9000, v148
	global_load_dwordx4 v[224:227], v247, s[14:15] offset:16
	global_load_dwordx4 v[228:231], v247, s[14:15]
	v_add_u32_e32 v247, 0xa000, v148
	global_load_dwordx4 v[248:251], v247, s[14:15] offset:16
	global_load_dwordx4 v[252:255], v247, s[14:15]
	v_add_u32_e32 v212, 0xb000, v148
	v_readlane_b32 s2, v246, 26
	s_cmp_gt_i32 s4, 1
	v_readlane_b32 s3, v246, 27
	v_or_b32_e32 v161, 16, v160
	v_ashrrev_i32_e32 v151, 31, v136
	v_mov_b64_e32 v[148:149], s[2:3]
	s_cselect_b64 s[2:3], -1, 0
	v_mov_b32_e32 v150, v136
	v_cndmask_b32_e64 v136, v159, 1.0, s[2:3]
	v_lshlrev_b32_e32 v180, 3, v161
	v_pk_mul_f32 v[126:127], v[136:137], v[126:127] op_sel_hi:[0,1]
	v_pk_mul_f32 v[172:173], v[136:137], v[124:125] op_sel_hi:[0,1]
	v_pk_mul_f32 v[122:123], v[136:137], v[122:123] op_sel_hi:[0,1]
	v_pk_mul_f32 v[174:175], v[136:137], v[120:121] op_sel_hi:[0,1]
	v_pk_mul_f32 v[118:119], v[136:137], v[118:119] op_sel_hi:[0,1]
	v_pk_mul_f32 v[176:177], v[136:137], v[116:117] op_sel_hi:[0,1]
	v_pk_mul_f32 v[114:115], v[136:137], v[114:115] op_sel_hi:[0,1]
	v_pk_mul_f32 v[178:179], v[136:137], v[112:113] op_sel_hi:[0,1]
	v_and_or_b32 v112, v180, s54, v155
	v_mad_i64_i32 v[170:171], s[2:3], v160, s51, v[148:149]
	v_lshlrev_b64 v[150:151], 1, v[150:151]
	v_lshlrev_b32_e32 v186, 5, v112
	v_lshl_add_u64 v[170:171], v[170:171], 0, v[150:151]
	v_pk_mul_f32 v[110:111], v[136:137], v[110:111] op_sel_hi:[0,1]
	v_pk_mul_f32 v[106:107], v[136:137], v[106:107] op_sel_hi:[0,1]
	v_pk_mul_f32 v[102:103], v[136:137], v[102:103] op_sel_hi:[0,1]
	v_pk_mul_f32 v[98:99], v[136:137], v[98:99] op_sel_hi:[0,1]
	v_pk_mul_f32 v[94:95], v[136:137], v[94:95] op_sel_hi:[0,1]
	v_pk_mul_f32 v[90:91], v[136:137], v[90:91] op_sel_hi:[0,1]
	v_pk_mul_f32 v[86:87], v[136:137], v[86:87] op_sel_hi:[0,1]
	v_pk_mul_f32 v[82:83], v[136:137], v[82:83] op_sel_hi:[0,1]
	v_pk_mul_f32 v[78:79], v[136:137], v[78:79] op_sel_hi:[0,1]
	v_pk_mul_f32 v[74:75], v[136:137], v[74:75] op_sel_hi:[0,1]
	v_pk_mul_f32 v[70:71], v[136:137], v[70:71] op_sel_hi:[0,1]
	v_pk_mul_f32 v[66:67], v[136:137], v[66:67] op_sel_hi:[0,1]
	v_pk_mul_f32 v[62:63], v[136:137], v[62:63] op_sel_hi:[0,1]
	v_pk_mul_f32 v[58:59], v[136:137], v[58:59] op_sel_hi:[0,1]
	v_pk_mul_f32 v[54:55], v[136:137], v[54:55] op_sel_hi:[0,1]
	v_pk_mul_f32 v[50:51], v[136:137], v[50:51] op_sel_hi:[0,1]
	v_pk_mul_f32 v[46:47], v[136:137], v[46:47] op_sel_hi:[0,1]
	v_pk_mul_f32 v[42:43], v[136:137], v[42:43] op_sel_hi:[0,1]
	v_pk_mul_f32 v[38:39], v[136:137], v[38:39] op_sel_hi:[0,1]
	v_pk_mul_f32 v[34:35], v[136:137], v[34:35] op_sel_hi:[0,1]
	v_pk_mul_f32 v[30:31], v[136:137], v[30:31] op_sel_hi:[0,1]
	v_pk_mul_f32 v[26:27], v[136:137], v[26:27] op_sel_hi:[0,1]
	v_pk_mul_f32 v[22:23], v[136:137], v[22:23] op_sel_hi:[0,1]
	v_pk_mul_f32 v[18:19], v[136:137], v[18:19] op_sel_hi:[0,1]
	v_pk_mul_f32 v[14:15], v[136:137], v[14:15] op_sel_hi:[0,1]
	v_pk_mul_f32 v[10:11], v[136:137], v[10:11] op_sel_hi:[0,1]
	v_pk_mul_f32 v[6:7], v[136:137], v[6:7] op_sel_hi:[0,1]
	v_pk_mul_f32 v[2:3], v[136:137], v[2:3] op_sel_hi:[0,1]
	s_cmp_lt_i32 s4, 2
	s_waitcnt vmcnt(12)
	v_pk_mul_f32 v[112:113], v[122:123], v[164:165]
	v_pk_mul_f32 v[116:117], v[174:175], v[162:163]
	v_pk_mul_f32 v[120:121], v[126:127], v[164:165]
	v_pk_mul_f32 v[180:181], v[172:173], v[162:163]
	v_pk_mul_f32 v[182:183], v[114:115], v[164:165]
	v_pk_mul_f32 v[184:185], v[178:179], v[162:163]
	v_pk_mul_f32 v[164:165], v[118:119], v[164:165]
	v_pk_mul_f32 v[162:163], v[176:177], v[162:163]
	v_pk_fma_f32 v[124:125], v[126:127], v[168:169], v[112:113] neg_lo:[0,0,1] neg_hi:[0,0,1]
	v_pk_fma_f32 v[126:127], v[172:173], v[166:167], v[116:117] neg_lo:[0,0,1] neg_hi:[0,0,1]
	v_pk_fma_f32 v[120:121], v[122:123], v[168:169], v[120:121]
	v_pk_fma_f32 v[122:123], v[174:175], v[166:167], v[180:181]
	v_pk_fma_f32 v[112:113], v[114:115], v[168:169], v[164:165]
	v_pk_fma_f32 v[114:115], v[178:179], v[166:167], v[162:163]
	v_cvt_pk_bf16_f32 v162, v126, v127
	v_cvt_pk_bf16_f32 v163, v124, v125
	v_cvt_pk_bf16_f32 v164, v122, v123
	v_cvt_pk_bf16_f32 v165, v120, v121
	v_pk_fma_f32 v[116:117], v[118:119], v[168:169], v[182:183] neg_lo:[0,0,1] neg_hi:[0,0,1]
	v_pk_fma_f32 v[118:119], v[176:177], v[166:167], v[184:185] neg_lo:[0,0,1] neg_hi:[0,0,1]
	global_store_dwordx4 v[170:171], v[162:165], off nt
	v_pk_mul_f32 v[172:173], v[136:137], v[108:109] op_sel_hi:[0,1]
	v_pk_mul_f32 v[174:175], v[136:137], v[104:105] op_sel_hi:[0,1]
	v_cvt_pk_bf16_f32 v162, v118, v119
	v_cvt_pk_bf16_f32 v163, v116, v117
	v_cvt_pk_bf16_f32 v164, v114, v115
	v_cvt_pk_bf16_f32 v165, v112, v113
	global_store_dwordx4 v[170:171], v[162:165], off offset:256 nt
	s_nop 1
	s_waitcnt vmcnt(12)
	v_mov_b32_e32 v162, v188
	v_mov_b32_e32 v163, v189
	v_mov_b32_e32 v164, v190
	v_mov_b32_e32 v165, v191
	s_nop 0
	v_mov_b32_e32 v166, v192
	v_mov_b32_e32 v167, v193
	v_mov_b32_e32 v168, v194
	v_mov_b32_e32 v169, v195
	global_load_dwordx4 v[188:191], v212, s[14:15] offset:16
	global_load_dwordx4 v[192:195], v212, s[14:15]
	v_or_b32_e32 v186, 32, v160
	v_mad_i64_i32 v[170:171], s[2:3], v161, s51, v[148:149]
	v_lshlrev_b32_e32 v161, 3, v186
	v_pk_mul_f32 v[176:177], v[136:137], v[100:101] op_sel_hi:[0,1]
	v_pk_mul_f32 v[178:179], v[136:137], v[96:97] op_sel_hi:[0,1]
	v_and_or_b32 v96, v161, s55, v155
	v_lshlrev_b32_e32 v161, 5, v96
	v_lshl_add_u64 v[170:171], v[170:171], 0, v[150:151]
	v_pk_mul_f32 v[96:97], v[106:107], v[164:165]
	v_pk_mul_f32 v[100:101], v[174:175], v[162:163]
	v_pk_mul_f32 v[104:105], v[110:111], v[164:165]
	v_pk_mul_f32 v[180:181], v[172:173], v[162:163]
	v_pk_mul_f32 v[182:183], v[98:99], v[164:165]
	v_pk_mul_f32 v[184:185], v[178:179], v[162:163]
	v_pk_mul_f32 v[164:165], v[102:103], v[164:165]
	v_pk_mul_f32 v[162:163], v[176:177], v[162:163]
	v_pk_fma_f32 v[108:109], v[110:111], v[168:169], v[96:97] neg_lo:[0,0,1] neg_hi:[0,0,1]
	v_pk_fma_f32 v[110:111], v[172:173], v[166:167], v[100:101] neg_lo:[0,0,1] neg_hi:[0,0,1]
	v_pk_fma_f32 v[104:105], v[106:107], v[168:169], v[104:105]
	v_pk_fma_f32 v[106:107], v[174:175], v[166:167], v[180:181]
	v_pk_fma_f32 v[96:97], v[98:99], v[168:169], v[164:165]
	v_pk_fma_f32 v[98:99], v[178:179], v[166:167], v[162:163]
	v_cvt_pk_bf16_f32 v162, v110, v111
	v_cvt_pk_bf16_f32 v163, v108, v109
	v_cvt_pk_bf16_f32 v164, v106, v107
	v_cvt_pk_bf16_f32 v165, v104, v105
	v_pk_fma_f32 v[100:101], v[102:103], v[168:169], v[182:183] neg_lo:[0,0,1] neg_hi:[0,0,1]
	v_pk_fma_f32 v[102:103], v[176:177], v[166:167], v[184:185] neg_lo:[0,0,1] neg_hi:[0,0,1]
	global_store_dwordx4 v[170:171], v[162:165], off nt
	v_pk_mul_f32 v[172:173], v[136:137], v[92:93] op_sel_hi:[0,1]
	v_pk_mul_f32 v[174:175], v[136:137], v[88:89] op_sel_hi:[0,1]
	v_cvt_pk_bf16_f32 v162, v102, v103
	v_cvt_pk_bf16_f32 v163, v100, v101
	v_cvt_pk_bf16_f32 v164, v98, v99
	v_cvt_pk_bf16_f32 v165, v96, v97
	global_store_dwordx4 v[170:171], v[162:165], off offset:256 nt
	s_nop 1
	s_waitcnt vmcnt(14)
	v_mov_b32_e32 v162, v196
	v_mov_b32_e32 v163, v197
	v_mov_b32_e32 v164, v198
	v_mov_b32_e32 v165, v199
	s_nop 0
	v_mov_b32_e32 v166, v200
	v_mov_b32_e32 v167, v201
	v_mov_b32_e32 v168, v202
	v_mov_b32_e32 v169, v203
	v_or_b32_e32 v161, 48, v160
	v_lshlrev_b32_e32 v180, 3, v161
	v_pk_mul_f32 v[176:177], v[136:137], v[84:85] op_sel_hi:[0,1]
	v_pk_mul_f32 v[178:179], v[136:137], v[80:81] op_sel_hi:[0,1]
	v_and_or_b32 v80, v180, s56, v155
	v_mad_i64_i32 v[170:171], s[2:3], v186, s51, v[148:149]
	v_lshlrev_b32_e32 v186, 5, v80
	v_lshl_add_u64 v[170:171], v[170:171], 0, v[150:151]
	v_pk_mul_f32 v[80:81], v[90:91], v[164:165]
	v_pk_mul_f32 v[84:85], v[174:175], v[162:163]
	v_pk_mul_f32 v[88:89], v[94:95], v[164:165]
	v_pk_mul_f32 v[180:181], v[172:173], v[162:163]
	v_pk_mul_f32 v[182:183], v[82:83], v[164:165]
	v_pk_mul_f32 v[184:185], v[178:179], v[162:163]
	v_pk_mul_f32 v[164:165], v[86:87], v[164:165]
	v_pk_mul_f32 v[162:163], v[176:177], v[162:163]
	v_pk_fma_f32 v[92:93], v[94:95], v[168:169], v[80:81] neg_lo:[0,0,1] neg_hi:[0,0,1]
	v_pk_fma_f32 v[94:95], v[172:173], v[166:167], v[84:85] neg_lo:[0,0,1] neg_hi:[0,0,1]
	v_pk_fma_f32 v[88:89], v[90:91], v[168:169], v[88:89]
	v_pk_fma_f32 v[90:91], v[174:175], v[166:167], v[180:181]
	v_pk_fma_f32 v[80:81], v[82:83], v[168:169], v[164:165]
	v_pk_fma_f32 v[82:83], v[178:179], v[166:167], v[162:163]
	v_cvt_pk_bf16_f32 v162, v94, v95
	v_cvt_pk_bf16_f32 v163, v92, v93
	v_cvt_pk_bf16_f32 v164, v90, v91
	v_cvt_pk_bf16_f32 v165, v88, v89
	v_pk_fma_f32 v[84:85], v[86:87], v[168:169], v[182:183] neg_lo:[0,0,1] neg_hi:[0,0,1]
	v_pk_fma_f32 v[86:87], v[176:177], v[166:167], v[184:185] neg_lo:[0,0,1] neg_hi:[0,0,1]
	global_store_dwordx4 v[170:171], v[162:165], off nt
	v_pk_mul_f32 v[172:173], v[136:137], v[76:77] op_sel_hi:[0,1]
	v_pk_mul_f32 v[174:175], v[136:137], v[72:73] op_sel_hi:[0,1]
	v_cvt_pk_bf16_f32 v162, v86, v87
	v_cvt_pk_bf16_f32 v163, v84, v85
	v_cvt_pk_bf16_f32 v164, v82, v83
	v_cvt_pk_bf16_f32 v165, v80, v81
	global_store_dwordx4 v[170:171], v[162:165], off offset:256 nt
	s_nop 1
	s_waitcnt vmcnt(14)
	v_mov_b32_e32 v162, v204
	v_mov_b32_e32 v163, v205
	v_mov_b32_e32 v164, v206
	v_mov_b32_e32 v165, v207
	s_nop 0
	v_mov_b32_e32 v166, v208
	v_mov_b32_e32 v167, v209
	v_mov_b32_e32 v168, v210
	v_mov_b32_e32 v169, v211
	v_add_u32_e32 v186, 0x80, v160
	v_mad_i64_i32 v[170:171], s[2:3], v161, s51, v[148:149]
	v_lshlrev_b32_e32 v161, 3, v186
	v_pk_mul_f32 v[176:177], v[136:137], v[68:69] op_sel_hi:[0,1]
	v_pk_mul_f32 v[178:179], v[136:137], v[64:65] op_sel_hi:[0,1]
	v_and_or_b32 v64, v161, s53, v155
	v_lshlrev_b32_e32 v161, 5, v64
	v_lshl_add_u64 v[170:171], v[170:171], 0, v[150:151]
	v_pk_mul_f32 v[64:65], v[74:75], v[164:165]
	v_pk_mul_f32 v[68:69], v[174:175], v[162:163]
	v_pk_mul_f32 v[72:73], v[78:79], v[164:165]
	v_pk_mul_f32 v[180:181], v[172:173], v[162:163]
	v_pk_mul_f32 v[182:183], v[66:67], v[164:165]
	v_pk_mul_f32 v[184:185], v[178:179], v[162:163]
	v_pk_mul_f32 v[164:165], v[70:71], v[164:165]
	v_pk_mul_f32 v[162:163], v[176:177], v[162:163]
	v_pk_fma_f32 v[76:77], v[78:79], v[168:169], v[64:65] neg_lo:[0,0,1] neg_hi:[0,0,1]
	v_pk_fma_f32 v[78:79], v[172:173], v[166:167], v[68:69] neg_lo:[0,0,1] neg_hi:[0,0,1]
	v_pk_fma_f32 v[72:73], v[74:75], v[168:169], v[72:73]
	v_pk_fma_f32 v[74:75], v[174:175], v[166:167], v[180:181]
	v_pk_fma_f32 v[64:65], v[66:67], v[168:169], v[164:165]
	v_pk_fma_f32 v[66:67], v[178:179], v[166:167], v[162:163]
	v_cvt_pk_bf16_f32 v162, v78, v79
	v_cvt_pk_bf16_f32 v163, v76, v77
	v_cvt_pk_bf16_f32 v164, v74, v75
	v_cvt_pk_bf16_f32 v165, v72, v73
	v_pk_fma_f32 v[68:69], v[70:71], v[168:169], v[182:183] neg_lo:[0,0,1] neg_hi:[0,0,1]
	v_pk_fma_f32 v[70:71], v[176:177], v[166:167], v[184:185] neg_lo:[0,0,1] neg_hi:[0,0,1]
	global_store_dwordx4 v[170:171], v[162:165], off nt
	v_pk_mul_f32 v[172:173], v[136:137], v[60:61] op_sel_hi:[0,1]
	v_pk_mul_f32 v[174:175], v[136:137], v[56:57] op_sel_hi:[0,1]
	v_cvt_pk_bf16_f32 v162, v70, v71
	v_cvt_pk_bf16_f32 v163, v68, v69
	v_cvt_pk_bf16_f32 v164, v66, v67
	v_cvt_pk_bf16_f32 v165, v64, v65
	global_store_dwordx4 v[170:171], v[162:165], off offset:256 nt
	s_nop 1
	s_waitcnt vmcnt(14)
	v_mov_b32_e32 v162, v216
	v_mov_b32_e32 v163, v217
	v_mov_b32_e32 v164, v218
	v_mov_b32_e32 v165, v219
	s_nop 0
	v_mov_b32_e32 v166, v220
	v_mov_b32_e32 v167, v221
	v_mov_b32_e32 v168, v222
	v_mov_b32_e32 v169, v223
	v_add_u32_e32 v161, 0x90, v160
	v_lshlrev_b32_e32 v180, 3, v161
	v_pk_mul_f32 v[176:177], v[136:137], v[52:53] op_sel_hi:[0,1]
	v_pk_mul_f32 v[178:179], v[136:137], v[48:49] op_sel_hi:[0,1]
	v_and_or_b32 v48, v180, s54, v155
	v_mad_i64_i32 v[170:171], s[2:3], v186, s51, v[148:149]
	v_lshlrev_b32_e32 v186, 5, v48
	v_lshl_add_u64 v[170:171], v[170:171], 0, v[150:151]
	v_pk_mul_f32 v[48:49], v[58:59], v[164:165]
	v_pk_mul_f32 v[52:53], v[174:175], v[162:163]
	v_pk_mul_f32 v[56:57], v[62:63], v[164:165]
	v_pk_mul_f32 v[180:181], v[172:173], v[162:163]
	v_pk_mul_f32 v[182:183], v[50:51], v[164:165]
	v_pk_mul_f32 v[184:185], v[178:179], v[162:163]
	v_pk_mul_f32 v[164:165], v[54:55], v[164:165]
	v_pk_mul_f32 v[162:163], v[176:177], v[162:163]
	v_pk_fma_f32 v[60:61], v[62:63], v[168:169], v[48:49] neg_lo:[0,0,1] neg_hi:[0,0,1]
	v_pk_fma_f32 v[62:63], v[172:173], v[166:167], v[52:53] neg_lo:[0,0,1] neg_hi:[0,0,1]
	v_pk_fma_f32 v[56:57], v[58:59], v[168:169], v[56:57]
	v_pk_fma_f32 v[58:59], v[174:175], v[166:167], v[180:181]
	v_pk_fma_f32 v[48:49], v[50:51], v[168:169], v[164:165]
	v_pk_fma_f32 v[50:51], v[178:179], v[166:167], v[162:163]
	v_cvt_pk_bf16_f32 v162, v62, v63
	v_cvt_pk_bf16_f32 v163, v60, v61
	v_cvt_pk_bf16_f32 v164, v58, v59
	v_cvt_pk_bf16_f32 v165, v56, v57
	v_pk_fma_f32 v[52:53], v[54:55], v[168:169], v[182:183] neg_lo:[0,0,1] neg_hi:[0,0,1]
	v_pk_fma_f32 v[54:55], v[176:177], v[166:167], v[184:185] neg_lo:[0,0,1] neg_hi:[0,0,1]
	global_store_dwordx4 v[170:171], v[162:165], off nt
	v_pk_mul_f32 v[172:173], v[136:137], v[44:45] op_sel_hi:[0,1]
	v_pk_mul_f32 v[174:175], v[136:137], v[40:41] op_sel_hi:[0,1]
	v_cvt_pk_bf16_f32 v162, v54, v55
	v_cvt_pk_bf16_f32 v163, v52, v53
	v_cvt_pk_bf16_f32 v164, v50, v51
	v_cvt_pk_bf16_f32 v165, v48, v49
	global_store_dwordx4 v[170:171], v[162:165], off offset:256 nt
	s_nop 1
	s_waitcnt vmcnt(14)
	v_mov_b32_e32 v162, v224
	v_mov_b32_e32 v163, v225
	v_mov_b32_e32 v164, v226
	v_mov_b32_e32 v165, v227
	s_nop 0
	v_mov_b32_e32 v166, v228
	v_mov_b32_e32 v167, v229
	v_mov_b32_e32 v168, v230
	v_mov_b32_e32 v169, v231
	v_add_u32_e32 v186, 0xa0, v160
	v_mad_i64_i32 v[170:171], s[2:3], v161, s51, v[148:149]
	v_lshlrev_b32_e32 v161, 3, v186
	v_pk_mul_f32 v[176:177], v[136:137], v[36:37] op_sel_hi:[0,1]
	v_pk_mul_f32 v[178:179], v[136:137], v[32:33] op_sel_hi:[0,1]
	v_and_or_b32 v32, v161, s55, v155
	v_lshlrev_b32_e32 v161, 5, v32
	v_lshl_add_u64 v[170:171], v[170:171], 0, v[150:151]
	v_pk_mul_f32 v[32:33], v[42:43], v[164:165]
	v_pk_mul_f32 v[36:37], v[174:175], v[162:163]
	v_pk_mul_f32 v[40:41], v[46:47], v[164:165]
	v_pk_mul_f32 v[180:181], v[172:173], v[162:163]
	v_pk_mul_f32 v[182:183], v[34:35], v[164:165]
	v_pk_mul_f32 v[184:185], v[178:179], v[162:163]
	v_pk_mul_f32 v[164:165], v[38:39], v[164:165]
	v_pk_mul_f32 v[162:163], v[176:177], v[162:163]
	v_pk_fma_f32 v[44:45], v[46:47], v[168:169], v[32:33] neg_lo:[0,0,1] neg_hi:[0,0,1]
	v_pk_fma_f32 v[46:47], v[172:173], v[166:167], v[36:37] neg_lo:[0,0,1] neg_hi:[0,0,1]
	v_pk_fma_f32 v[40:41], v[42:43], v[168:169], v[40:41]
	v_pk_fma_f32 v[42:43], v[174:175], v[166:167], v[180:181]
	v_pk_fma_f32 v[32:33], v[34:35], v[168:169], v[164:165]
	v_pk_fma_f32 v[34:35], v[178:179], v[166:167], v[162:163]
	v_cvt_pk_bf16_f32 v162, v46, v47
	v_cvt_pk_bf16_f32 v163, v44, v45
	v_cvt_pk_bf16_f32 v164, v42, v43
	v_cvt_pk_bf16_f32 v165, v40, v41
	v_pk_fma_f32 v[36:37], v[38:39], v[168:169], v[182:183] neg_lo:[0,0,1] neg_hi:[0,0,1]
	v_pk_fma_f32 v[38:39], v[176:177], v[166:167], v[184:185] neg_lo:[0,0,1] neg_hi:[0,0,1]
	global_store_dwordx4 v[170:171], v[162:165], off nt
	v_add_u32_e32 v184, 0xb0, v160
	v_lshlrev_b32_e32 v178, 3, v184
	v_cvt_pk_bf16_f32 v162, v38, v39
	v_cvt_pk_bf16_f32 v163, v36, v37
	v_cvt_pk_bf16_f32 v164, v34, v35
	v_cvt_pk_bf16_f32 v165, v32, v33
	global_store_dwordx4 v[170:171], v[162:165], off offset:256 nt
	s_nop 1
	s_waitcnt vmcnt(14)
	v_mov_b32_e32 v162, v248
	v_mov_b32_e32 v163, v249
	v_mov_b32_e32 v164, v250
	v_mov_b32_e32 v165, v251
	s_nop 0
	v_mov_b32_e32 v166, v252
	v_mov_b32_e32 v167, v253
	v_mov_b32_e32 v168, v254
	v_mov_b32_e32 v169, v255
	v_mad_i64_i32 v[160:161], s[2:3], v186, s51, v[148:149]
	v_lshl_add_u64 v[170:171], v[160:161], 0, v[150:151]
	v_pk_mul_f32 v[160:161], v[136:137], v[28:29] op_sel_hi:[0,1]
	v_pk_mul_f32 v[172:173], v[136:137], v[24:25] op_sel_hi:[0,1]
	v_pk_mul_f32 v[174:175], v[136:137], v[20:21] op_sel_hi:[0,1]
	v_pk_mul_f32 v[176:177], v[136:137], v[16:17] op_sel_hi:[0,1]
	v_and_or_b32 v16, v178, s56, v155
	v_lshlrev_b32_e32 v185, 5, v16
	v_mad_i64_i32 v[148:149], s[2:3], v184, s51, v[148:149]
	v_pk_mul_f32 v[16:17], v[26:27], v[164:165]
	v_pk_mul_f32 v[20:21], v[172:173], v[162:163]
	v_pk_mul_f32 v[24:25], v[30:31], v[164:165]
	v_pk_mul_f32 v[178:179], v[160:161], v[162:163]
	v_pk_mul_f32 v[180:181], v[18:19], v[164:165]
	v_pk_mul_f32 v[182:183], v[176:177], v[162:163]
	v_pk_mul_f32 v[164:165], v[22:23], v[164:165]
	v_pk_mul_f32 v[162:163], v[174:175], v[162:163]
	v_pk_fma_f32 v[28:29], v[30:31], v[168:169], v[16:17] neg_lo:[0,0,1] neg_hi:[0,0,1]
	v_pk_fma_f32 v[30:31], v[160:161], v[166:167], v[20:21] neg_lo:[0,0,1] neg_hi:[0,0,1]
	v_pk_fma_f32 v[24:25], v[26:27], v[168:169], v[24:25]
	v_pk_fma_f32 v[26:27], v[172:173], v[166:167], v[178:179]
	v_pk_fma_f32 v[16:17], v[18:19], v[168:169], v[164:165]
	v_pk_fma_f32 v[18:19], v[176:177], v[166:167], v[162:163]
	v_cvt_pk_bf16_f32 v160, v30, v31
	v_cvt_pk_bf16_f32 v161, v28, v29
	v_cvt_pk_bf16_f32 v162, v26, v27
	v_cvt_pk_bf16_f32 v163, v24, v25
	v_pk_fma_f32 v[20:21], v[22:23], v[168:169], v[180:181] neg_lo:[0,0,1] neg_hi:[0,0,1]
	v_pk_fma_f32 v[22:23], v[174:175], v[166:167], v[182:183] neg_lo:[0,0,1] neg_hi:[0,0,1]
	global_store_dwordx4 v[170:171], v[160:163], off nt
	v_lshl_add_u64 v[168:169], v[148:149], 0, v[150:151]
	v_pk_mul_f32 v[148:149], v[136:137], v[12:13] op_sel_hi:[0,1]
	v_cvt_pk_bf16_f32 v160, v22, v23
	v_cvt_pk_bf16_f32 v161, v20, v21
	v_cvt_pk_bf16_f32 v162, v18, v19
	v_cvt_pk_bf16_f32 v163, v16, v17
	global_store_dwordx4 v[170:171], v[160:163], off offset:256 nt
	s_nop 1
	s_waitcnt vmcnt(12)
	v_mov_b32_e32 v160, v188
	v_mov_b32_e32 v161, v189
	v_mov_b32_e32 v162, v190
	v_mov_b32_e32 v163, v191
	s_nop 0
	v_mov_b32_e32 v164, v192
	v_mov_b32_e32 v165, v193
	v_mov_b32_e32 v166, v194
	v_mov_b32_e32 v167, v195
	v_pk_mul_f32 v[150:151], v[136:137], v[8:9] op_sel_hi:[0,1]
	v_pk_mul_f32 v[170:171], v[136:137], v[4:5] op_sel_hi:[0,1]
	v_pk_mul_f32 v[172:173], v[136:137], v[0:1] op_sel_hi:[0,1]
	v_pk_mul_f32 v[0:1], v[10:11], v[162:163]
	v_pk_mul_f32 v[4:5], v[150:151], v[160:161]
	v_pk_mul_f32 v[8:9], v[14:15], v[162:163]
	v_pk_mul_f32 v[174:175], v[148:149], v[160:161]
	v_pk_mul_f32 v[176:177], v[2:3], v[162:163]
	v_pk_mul_f32 v[178:179], v[172:173], v[160:161]
	v_pk_mul_f32 v[162:163], v[6:7], v[162:163]
	v_pk_mul_f32 v[160:161], v[170:171], v[160:161]
	v_pk_fma_f32 v[12:13], v[14:15], v[166:167], v[0:1] neg_lo:[0,0,1] neg_hi:[0,0,1]
	v_pk_fma_f32 v[14:15], v[148:149], v[164:165], v[4:5] neg_lo:[0,0,1] neg_hi:[0,0,1]
	v_pk_fma_f32 v[8:9], v[10:11], v[166:167], v[8:9]
	v_pk_fma_f32 v[10:11], v[150:151], v[164:165], v[174:175]
	v_pk_fma_f32 v[4:5], v[6:7], v[166:167], v[176:177] neg_lo:[0,0,1] neg_hi:[0,0,1]
	v_pk_fma_f32 v[6:7], v[170:171], v[164:165], v[178:179] neg_lo:[0,0,1] neg_hi:[0,0,1]
	v_pk_fma_f32 v[0:1], v[2:3], v[166:167], v[162:163]
	v_pk_fma_f32 v[2:3], v[172:173], v[164:165], v[160:161]
	v_cvt_pk_bf16_f32 v148, v14, v15
	v_cvt_pk_bf16_f32 v149, v12, v13
	v_cvt_pk_bf16_f32 v150, v10, v11
	v_cvt_pk_bf16_f32 v151, v8, v9
	global_store_dwordx4 v[168:169], v[148:151], off nt
	s_nop 1
	v_cvt_pk_bf16_f32 v148, v6, v7
	v_cvt_pk_bf16_f32 v149, v4, v5
	v_cvt_pk_bf16_f32 v150, v2, v3
	v_cvt_pk_bf16_f32 v151, v0, v1
	global_store_dwordx4 v[168:169], v[148:151], off offset:256 nt
	s_cbranch_scc1 .LBB0_291
	v_pk_add_f32 v[126:127], v[126:127], 0 op_sel_hi:[1,0]
	s_add_i32 s4, s1, 0xfffffe00
	v_pk_add_f32 v[110:111], v[126:127], v[110:111]
	s_nop 0
	v_pk_add_f32 v[94:95], v[110:111], v[94:95]
	s_nop 0
	v_pk_add_f32 v[78:79], v[94:95], v[78:79]
	s_nop 0
	v_pk_add_f32 v[62:63], v[78:79], v[62:63]
	s_nop 0
	v_pk_add_f32 v[46:47], v[62:63], v[46:47]
	s_nop 0
	v_pk_add_f32 v[30:31], v[46:47], v[30:31]
	s_nop 0
	v_pk_add_f32 v[14:15], v[30:31], v[14:15]
	v_mov_b32_e32 v31, v137
	s_nop 0
	v_add_f32_dpp v14, v14, v14 row_ror:8 row_mask:0xf bank_mask:0xf bound_ctrl:1
	s_nop 1
	v_add_f32_dpp v14, v14, v14 row_ror:4 row_mask:0xf bank_mask:0xf bound_ctrl:1
	s_nop 1
	v_add_f32_dpp v30, v14, v14 row_ror:2 row_mask:0xf bank_mask:0xf bound_ctrl:1
	v_lshlrev_b32_e32 v14, 2, v138
	s_nop 0
	v_mov_b32_dpp v31, v30 row_ror:1 row_mask:0xf bank_mask:0xf
	s_and_saveexec_b64 s[2:3], s[6:7]
	s_cbranch_execz .LBB0_260
	s_ashr_i32 s1, s0, 31
	s_lshl_b64 s[10:11], s[0:1], 11
	s_add_u32 s1, s16, s10
	s_addc_u32 s27, s17, s11
	s_lshl_b64 s[10:11], s[4:5], 2
	s_add_u32 s1, s1, s10
	s_addc_u32 s11, s27, s11
	s_lshl_b32 s10, s42, 2
	s_add_u32 s10, s1, s10
	v_add_f32_e32 v30, v30, v31
	s_addc_u32 s11, s11, 0
	global_atomic_add_f32 v14, v30, s[10:11]
